# ping-pong attention with ONE barrier per tile per wave: group A syncs only after its softmax phase, group B only after its MFMA phase (the other barrier of each group was not needed for LDS reuse or d
# speedup vs baseline: 1.0152x; 1.0095x over previous
.LBB0_1183:
	s_andn2_b64 s[42:43], exec, s[70:71]
	v_exp_f32_e32 v96, v96
	v_exp_f32_e32 v80, v80
	v_exp_f32_e32 v97, v97
	v_exp_f32_e32 v81, v81
	v_add_f32_e32 v9, 0, v96
	v_exp_f32_e32 v98, v98
	v_add_f32_e32 v9, v80, v9
	v_exp_f32_e32 v82, v82
	v_add_f32_e32 v9, v97, v9
	v_exp_f32_e32 v99, v99
	v_add_f32_e32 v9, v81, v9
	v_exp_f32_e32 v83, v83
	v_add_f32_e32 v9, v98, v9
	v_exp_f32_e32 v100, v100
	v_add_f32_e32 v9, v82, v9
	v_exp_f32_e32 v84, v84
	v_add_f32_e32 v9, v99, v9
	v_exp_f32_e32 v101, v101
	v_add_f32_e32 v9, v83, v9
	v_exp_f32_e32 v85, v85
	v_add_f32_e32 v9, v100, v9
	v_exp_f32_e32 v102, v102
	v_add_f32_e32 v9, v84, v9
	v_exp_f32_e32 v86, v86
	v_add_f32_e32 v9, v101, v9
	v_exp_f32_e32 v103, v103
	v_add_f32_e32 v9, v85, v9
	v_exp_f32_e32 v87, v87
	v_add_f32_e32 v9, v102, v9
	v_exp_f32_e32 v104, v104
	v_add_f32_e32 v9, v86, v9
	v_exp_f32_e32 v88, v88
	v_add_f32_e32 v9, v103, v9
	v_exp_f32_e32 v105, v105
	v_add_f32_e32 v9, v87, v9
	v_exp_f32_e32 v89, v89
	v_add_f32_e32 v9, v104, v9
	v_exp_f32_e32 v106, v106
	v_add_f32_e32 v9, v88, v9
	v_exp_f32_e32 v90, v90
	v_add_f32_e32 v9, v105, v9
	v_exp_f32_e32 v107, v107
	v_add_f32_e32 v9, v89, v9
	v_exp_f32_e32 v91, v91
	v_add_f32_e32 v9, v106, v9
	v_exp_f32_e32 v108, v108
	v_add_f32_e32 v9, v90, v9
	v_exp_f32_e32 v92, v92
	v_add_f32_e32 v9, v107, v9
	v_exp_f32_e32 v109, v109
	v_add_f32_e32 v9, v91, v9
	v_exp_f32_e32 v93, v93
	v_add_f32_e32 v9, v108, v9
	v_exp_f32_e32 v110, v110
	v_add_f32_e32 v9, v92, v9
	v_exp_f32_e32 v94, v94
	v_add_f32_e32 v9, v109, v9
	v_exp_f32_e32 v111, v111
	v_add_f32_e32 v9, v93, v9
	v_exp_f32_e32 v95, v95
	v_add_f32_e32 v9, v110, v9
	v_add_f32_e32 v9, v94, v9
	v_add_f32_e32 v9, v111, v9
	v_add_f32_e32 v9, v95, v9
	v_add_f32_e32 v161, v161, v9
	v_cvt_pk_bf16_f32 v96, v96, v97
	v_cvt_pk_bf16_f32 v97, v98, v99
	v_cvt_pk_bf16_f32 v98, v100, v101
	v_cvt_pk_bf16_f32 v99, v102, v103
	v_cvt_pk_bf16_f32 v100, v104, v105
	v_cvt_pk_bf16_f32 v101, v106, v107
	v_cvt_pk_bf16_f32 v102, v108, v109
	v_cvt_pk_bf16_f32 v103, v110, v111
	v_cvt_pk_bf16_f32 v80, v80, v81
	v_cvt_pk_bf16_f32 v81, v82, v83
	v_cvt_pk_bf16_f32 v82, v84, v85
	v_cvt_pk_bf16_f32 v83, v86, v87
	v_cvt_pk_bf16_f32 v84, v88, v89
	v_cvt_pk_bf16_f32 v85, v90, v91
	v_cvt_pk_bf16_f32 v86, v92, v93
	v_cvt_pk_bf16_f32 v87, v94, v95
	s_cmp_lg_u32 s19, 0
	s_cbranch_scc1 .Lpp_a0_done
	s_waitcnt vmcnt(0)
	s_barrier
	s_and_b64 vcc, exec, s[66:67]
	s_cbranch_vccnz .Lpp_a0_v
	s_add_u32 s0, s62, 0xfffe0000
	s_addc_u32 s1, s63, -1
	s_mov_b32 m0, s21
	s_nop 0
	global_load_lds_dwordx4 v150, s[0:1]
	s_mov_b32 m0, s22
	s_nop 0
	global_load_lds_dwordx4 v144, s[0:1]

.LBB0_1185:
	ds_read_b64_tr_b16 v[178:179], v166 offset:36864
	ds_read_b64_tr_b16 v[180:181], v158 offset:36864
	ds_read_b64_tr_b16 v[182:183], v167 offset:36864
	ds_read_b64_tr_b16 v[184:185], v160 offset:36864
	ds_read_b64_tr_b16 v[186:187], v168 offset:36864
	ds_read_b64_tr_b16 v[188:189], v162 offset:36864
	ds_read_b64_tr_b16 v[190:191], v169 offset:36864
	ds_read_b64_tr_b16 v[192:193], v163 offset:36864
	s_waitcnt lgkmcnt(14)
	s_nop 0
	v_mfma_f32_32x32x16_bf16 v[48:63], v[104:107], v[96:99], v[48:63]
	s_waitcnt lgkmcnt(12)
	v_mfma_f32_32x32x16_bf16 v[64:79], v[108:111], v[96:99], v[64:79]
	s_waitcnt lgkmcnt(10)
	v_mfma_f32_32x32x16_bf16 v[32:47], v[88:91], v[96:99], v[32:47]
	s_waitcnt lgkmcnt(8)
	v_mfma_f32_32x32x16_bf16 v[16:31], v[92:95], v[96:99], v[16:31]
	ds_read_b64_tr_b16 v[0:1], v166 offset:40960
	ds_read_b64_tr_b16 v[2:3], v158 offset:40960
	ds_read_b64_tr_b16 v[4:5], v167 offset:40960
	ds_read_b64_tr_b16 v[6:7], v160 offset:40960
	ds_read_b64_tr_b16 v[10:11], v168 offset:40960
	ds_read_b64_tr_b16 v[12:13], v162 offset:40960
	ds_read_b64_tr_b16 v[174:175], v169 offset:40960
	ds_read_b64_tr_b16 v[176:177], v163 offset:40960
	s_waitcnt lgkmcnt(14)
	s_nop 0
	v_mfma_f32_32x32x16_bf16 v[48:63], v[178:181], v[100:103], v[48:63]
	s_waitcnt lgkmcnt(12)
	v_mfma_f32_32x32x16_bf16 v[64:79], v[182:185], v[100:103], v[64:79]
	s_waitcnt lgkmcnt(10)
	v_mfma_f32_32x32x16_bf16 v[32:47], v[186:189], v[100:103], v[32:47]
	s_waitcnt lgkmcnt(8)
	v_mfma_f32_32x32x16_bf16 v[16:31], v[190:193], v[100:103], v[16:31]
	ds_read_b64_tr_b16 v[178:179], v166 offset:45056
	ds_read_b64_tr_b16 v[180:181], v158 offset:45056
	ds_read_b64_tr_b16 v[182:183], v167 offset:45056
	ds_read_b64_tr_b16 v[184:185], v160 offset:45056
	ds_read_b64_tr_b16 v[186:187], v168 offset:45056
	ds_read_b64_tr_b16 v[188:189], v162 offset:45056
	ds_read_b64_tr_b16 v[190:191], v169 offset:45056
	ds_read_b64_tr_b16 v[192:193], v163 offset:45056
	s_waitcnt lgkmcnt(14)
	s_nop 0
	v_mfma_f32_32x32x16_bf16 v[48:63], v[0:3], v[80:83], v[48:63]
	s_waitcnt lgkmcnt(12)
	v_mfma_f32_32x32x16_bf16 v[64:79], v[4:7], v[80:83], v[64:79]
	s_waitcnt lgkmcnt(10)
	v_mfma_f32_32x32x16_bf16 v[32:47], v[10:13], v[80:83], v[32:47]
	s_waitcnt lgkmcnt(8)
	v_mfma_f32_32x32x16_bf16 v[16:31], v[174:177], v[80:83], v[16:31]
	s_cmp_eq_u32 s19, 0
	s_cbranch_scc1 .Lpp_y0
	s_waitcnt vmcnt(0) lgkmcnt(0)
	s_barrier
.Lpp_y0:
	s_setprio 0
	s_waitcnt lgkmcnt(6)
	v_mfma_f32_32x32x16_bf16 v[48:63], v[178:181], v[84:87], v[48:63]
	s_and_b64 vcc, exec, s[42:43]
	s_waitcnt lgkmcnt(4)
	v_mfma_f32_32x32x16_bf16 v[64:79], v[182:185], v[84:87], v[64:79]
	s_waitcnt lgkmcnt(2)
	v_mfma_f32_32x32x16_bf16 v[32:47], v[186:189], v[84:87], v[32:47]
	s_waitcnt lgkmcnt(0)
	v_mfma_f32_32x32x16_bf16 v[16:31], v[190:193], v[84:87], v[16:31]
	s_cbranch_vccnz .LBB0_1197
	s_andn2_b64 s[42:43], exec, s[68:69]
	s_cmp_eq_u32 s19, 0
	s_cbranch_scc1 .LBB0_1188
	s_add_i32 s3, s74, 3
	s_cmp_ge_u32 s3, s17
	s_cbranch_scc1 .Lpp_b1_v
	s_mov_b32 m0, s27
	s_nop 0
	global_load_lds_dwordx4 v150, s[62:63]
	s_add_i32 m0, s27, 0x400
	s_nop 0
	global_load_lds_dwordx4 v144, s[62:63]

.LBB0_1194:
	v_exp_f32_e32 v128, v128
	v_exp_f32_e32 v112, v112
	v_exp_f32_e32 v129, v129
	v_exp_f32_e32 v113, v113
	v_add_f32_e32 v9, 0, v128
	v_exp_f32_e32 v130, v130
	v_add_f32_e32 v9, v112, v9
	v_exp_f32_e32 v114, v114
	v_add_f32_e32 v9, v129, v9
	v_exp_f32_e32 v131, v131
	v_add_f32_e32 v9, v113, v9
	v_exp_f32_e32 v115, v115
	v_add_f32_e32 v9, v130, v9
	v_exp_f32_e32 v132, v132
	v_add_f32_e32 v9, v114, v9
	v_exp_f32_e32 v116, v116
	v_add_f32_e32 v9, v131, v9
	v_exp_f32_e32 v133, v133
	v_add_f32_e32 v9, v115, v9
	v_exp_f32_e32 v117, v117
	v_add_f32_e32 v9, v132, v9
	v_exp_f32_e32 v134, v134
	v_add_f32_e32 v9, v116, v9
	v_exp_f32_e32 v118, v118
	v_add_f32_e32 v9, v133, v9
	v_exp_f32_e32 v135, v135
	v_add_f32_e32 v9, v117, v9
	v_exp_f32_e32 v119, v119
	v_add_f32_e32 v9, v134, v9
	v_exp_f32_e32 v136, v136
	v_add_f32_e32 v9, v118, v9
	v_exp_f32_e32 v120, v120
	v_add_f32_e32 v9, v135, v9
	v_exp_f32_e32 v137, v137
	v_add_f32_e32 v9, v119, v9
	v_exp_f32_e32 v121, v121
	v_add_f32_e32 v9, v136, v9
	v_exp_f32_e32 v138, v138
	v_add_f32_e32 v9, v120, v9
	v_exp_f32_e32 v122, v122
	v_add_f32_e32 v9, v137, v9
	v_exp_f32_e32 v139, v139
	v_add_f32_e32 v9, v121, v9
	v_exp_f32_e32 v123, v123
	v_add_f32_e32 v9, v138, v9
	v_exp_f32_e32 v140, v140
	v_add_f32_e32 v9, v122, v9
	v_exp_f32_e32 v124, v124
	v_add_f32_e32 v9, v139, v9
	v_exp_f32_e32 v141, v141
	v_add_f32_e32 v9, v123, v9
	v_exp_f32_e32 v125, v125
	v_add_f32_e32 v9, v140, v9
	v_exp_f32_e32 v142, v142
	v_add_f32_e32 v9, v124, v9
	v_exp_f32_e32 v126, v126
	v_add_f32_e32 v9, v141, v9
	v_exp_f32_e32 v143, v143
	v_add_f32_e32 v9, v125, v9
	v_exp_f32_e32 v127, v127
	v_add_f32_e32 v9, v142, v9
	v_add_f32_e32 v9, v126, v9
	v_add_f32_e32 v9, v143, v9
	v_add_f32_e32 v9, v127, v9
	v_add_f32_e32 v161, v161, v9
	v_cvt_pk_bf16_f32 v128, v128, v129
	v_cvt_pk_bf16_f32 v129, v130, v131
	v_cvt_pk_bf16_f32 v130, v132, v133
	v_cvt_pk_bf16_f32 v131, v134, v135
	v_cvt_pk_bf16_f32 v132, v136, v137
	v_cvt_pk_bf16_f32 v133, v138, v139
	v_cvt_pk_bf16_f32 v134, v140, v141
	v_cvt_pk_bf16_f32 v135, v142, v143
	v_cvt_pk_bf16_f32 v112, v112, v113
	v_cvt_pk_bf16_f32 v113, v114, v115
	v_cvt_pk_bf16_f32 v114, v116, v117
	v_cvt_pk_bf16_f32 v115, v118, v119
	v_cvt_pk_bf16_f32 v116, v120, v121
	v_cvt_pk_bf16_f32 v117, v122, v123
	v_cvt_pk_bf16_f32 v118, v124, v125
	v_cvt_pk_bf16_f32 v119, v126, v127
	s_cmp_lg_u32 s19, 0
	s_cbranch_scc1 .Lpp_a1_done
	s_waitcnt vmcnt(0)
	s_barrier
	s_add_i32 s3, s74, 3
	s_cmp_ge_u32 s3, s17
	s_cbranch_scc1 .Lpp_a1_v
	s_mov_b32 m0, s27
	s_nop 0
	global_load_lds_dwordx4 v150, s[62:63]
	s_add_i32 m0, s27, 0x400
	s_nop 0
	global_load_lds_dwordx4 v144, s[62:63]

.LBB0_1196:
	ds_read_b64_tr_b16 v[178:179], v166 offset:53248
	ds_read_b64_tr_b16 v[180:181], v158 offset:53248
	ds_read_b64_tr_b16 v[182:183], v167 offset:53248
	ds_read_b64_tr_b16 v[184:185], v160 offset:53248
	ds_read_b64_tr_b16 v[186:187], v168 offset:53248
	ds_read_b64_tr_b16 v[188:189], v162 offset:53248
	ds_read_b64_tr_b16 v[190:191], v169 offset:53248
	ds_read_b64_tr_b16 v[192:193], v163 offset:53248
	s_waitcnt lgkmcnt(14)
	s_nop 0
	v_mfma_f32_32x32x16_bf16 v[48:63], v[136:139], v[128:131], v[48:63]
	s_waitcnt lgkmcnt(12)
	v_mfma_f32_32x32x16_bf16 v[64:79], v[140:143], v[128:131], v[64:79]
	s_waitcnt lgkmcnt(10)
	v_mfma_f32_32x32x16_bf16 v[32:47], v[120:123], v[128:131], v[32:47]
	s_waitcnt lgkmcnt(8)
	v_mfma_f32_32x32x16_bf16 v[16:31], v[124:127], v[128:131], v[16:31]
	ds_read_b64_tr_b16 v[0:1], v166 offset:57344
	ds_read_b64_tr_b16 v[2:3], v158 offset:57344
	ds_read_b64_tr_b16 v[4:5], v167 offset:57344
	ds_read_b64_tr_b16 v[6:7], v160 offset:57344
	ds_read_b64_tr_b16 v[10:11], v168 offset:57344
	ds_read_b64_tr_b16 v[12:13], v162 offset:57344
	ds_read_b64_tr_b16 v[174:175], v169 offset:57344
	ds_read_b64_tr_b16 v[176:177], v163 offset:57344
	s_waitcnt lgkmcnt(14)
	s_nop 0
	v_mfma_f32_32x32x16_bf16 v[48:63], v[178:181], v[132:135], v[48:63]
	s_waitcnt lgkmcnt(12)
	v_mfma_f32_32x32x16_bf16 v[64:79], v[182:185], v[132:135], v[64:79]
	s_waitcnt lgkmcnt(10)
	v_mfma_f32_32x32x16_bf16 v[32:47], v[186:189], v[132:135], v[32:47]
	s_waitcnt lgkmcnt(8)
	v_mfma_f32_32x32x16_bf16 v[16:31], v[190:193], v[132:135], v[16:31]
	ds_read_b64_tr_b16 v[178:179], v166 offset:61440
	ds_read_b64_tr_b16 v[180:181], v158 offset:61440
	ds_read_b64_tr_b16 v[182:183], v167 offset:61440
	ds_read_b64_tr_b16 v[184:185], v160 offset:61440
	ds_read_b64_tr_b16 v[186:187], v168 offset:61440
	ds_read_b64_tr_b16 v[188:189], v162 offset:61440
	ds_read_b64_tr_b16 v[170:171], v169 offset:61440
	ds_read_b64_tr_b16 v[172:173], v163 offset:61440
	s_waitcnt lgkmcnt(14)
	s_nop 0
	v_mfma_f32_32x32x16_bf16 v[48:63], v[0:3], v[112:115], v[48:63]
	s_waitcnt lgkmcnt(12)
	v_mfma_f32_32x32x16_bf16 v[64:79], v[4:7], v[112:115], v[64:79]
	s_waitcnt lgkmcnt(10)
	v_mfma_f32_32x32x16_bf16 v[32:47], v[10:13], v[112:115], v[32:47]
	s_waitcnt lgkmcnt(8)
	v_mfma_f32_32x32x16_bf16 v[16:31], v[174:177], v[112:115], v[16:31]
	s_cmp_eq_u32 s19, 0
	s_cbranch_scc1 .Lpp_y1
	s_waitcnt vmcnt(0) lgkmcnt(0)
	s_barrier
.Lpp_y1:
	s_setprio 0
	s_waitcnt lgkmcnt(6)
	v_mfma_f32_32x32x16_bf16 v[48:63], v[178:181], v[116:119], v[48:63]
	s_waitcnt lgkmcnt(4)
	v_mfma_f32_32x32x16_bf16 v[64:79], v[182:185], v[116:119], v[64:79]
	s_waitcnt lgkmcnt(2)
	v_mfma_f32_32x32x16_bf16 v[32:47], v[186:189], v[116:119], v[32:47]
	s_waitcnt lgkmcnt(0)
	v_mfma_f32_32x32x16_bf16 v[16:31], v[170:173], v[116:119], v[16:31]
